# v28 + phase 0b skips layer-0 tiles that A(0)-start converts (w_uq, w_ukv, gates, w_out)
# speedup vs baseline: 1.0011x; 1.0008x over previous
.LBB0_41:
	s_cmpk_lt_u32 s60, 0x1a0
	s_cbranch_scc1 .Lmy_cvt0b_go
	s_cmpk_lt_u32 s60, 0x330
	s_cbranch_scc1 .LBB0_40
